# MLA softmax reference update triggered by the per-tile row sum exceeding 2^14 (exponent shift) instead of a per-tile max chain; exact softmax, same rescale path (verified with threshold 0)
# speedup vs baseline: 1.0430x; 1.0094x over previous
.Lmla_c0:
	ds_read_b128 v[152:155], v149
	ds_read_b128 v[156:159], v149 offset:32
	ds_read_b128 v[160:163], v149 offset:64
	ds_read_b128 v[164:167], v149 offset:96
	ds_read_b128 v[168:171], v149 offset:128
	ds_read_b128 v[172:175], v149 offset:160
	s_waitcnt lgkmcnt(5)
	v_mfma_f32_32x32x16_bf16 v[52:67], v[152:155], v[68:71], v[232:247]
	ds_read_b128 v[152:155], v149 offset:6656
	s_waitcnt lgkmcnt(5)
	v_mfma_f32_32x32x16_bf16 v[52:67], v[156:159], v[72:75], v[52:67]
	ds_read_b128 v[156:159], v149 offset:6688
	s_waitcnt lgkmcnt(5)
	v_mfma_f32_32x32x16_bf16 v[52:67], v[160:163], v[76:79], v[52:67]
	ds_read_b128 v[160:163], v149 offset:6720
	s_waitcnt lgkmcnt(5)
	v_mfma_f32_32x32x16_bf16 v[52:67], v[164:167], v[80:83], v[52:67]
	ds_read_b128 v[164:167], v149 offset:6752
	s_waitcnt lgkmcnt(5)
	v_mfma_f32_32x32x16_bf16 v[52:67], v[168:171], v[84:87], v[52:67]
	ds_read_b128 v[168:171], v149 offset:6784
	ds_read_b128 v[198:201], v150 offset:26624
	s_waitcnt lgkmcnt(6)
	v_mfma_f32_32x32x16_bf16 v[52:67], v[172:175], v[88:91], v[52:67]
	ds_read_b128 v[172:175], v149 offset:6816
	ds_read_b128 v[202:205], v150 offset:26656
	ds_read_b128 v[206:209], v150 offset:31232
	ds_read_b128 v[210:213], v150 offset:31264
	s_waitcnt lgkmcnt(9)
	v_mfma_f32_32x32x16_bf16 v[36:51], v[152:155], v[68:71], v[232:247]
	s_waitcnt lgkmcnt(8)
	v_mfma_f32_32x32x16_bf16 v[36:51], v[156:159], v[72:75], v[36:51]
	s_nop 3
	v_exp_f32_e32 v52, v52
	v_exp_f32_e32 v53, v53
	s_waitcnt lgkmcnt(7)
	v_mfma_f32_32x32x16_bf16 v[36:51], v[160:163], v[76:79], v[36:51]
	v_exp_f32_e32 v54, v54
	v_exp_f32_e32 v55, v55
	v_exp_f32_e32 v56, v56
	v_exp_f32_e32 v57, v57
	v_exp_f32_e32 v58, v58
	v_exp_f32_e32 v59, v59
	s_waitcnt lgkmcnt(6)
	v_mfma_f32_32x32x16_bf16 v[36:51], v[164:167], v[80:83], v[36:51]
	v_exp_f32_e32 v60, v60
	v_exp_f32_e32 v61, v61
	v_exp_f32_e32 v62, v62
	v_exp_f32_e32 v63, v63
	v_exp_f32_e32 v64, v64
	v_exp_f32_e32 v65, v65
	s_waitcnt lgkmcnt(5)
	v_mfma_f32_32x32x16_bf16 v[36:51], v[168:171], v[84:87], v[36:51]
	v_exp_f32_e32 v66, v66
	v_exp_f32_e32 v67, v67
	v_add_f32_e32 v176, v52, v53
	v_add_f32_e32 v176, v54, v176
	v_add_f32_e32 v176, v55, v176
	v_add_f32_e32 v176, v56, v176
	v_add_f32_e32 v176, v57, v176
	v_add_f32_e32 v176, v58, v176
	v_add_f32_e32 v176, v59, v176
	s_waitcnt lgkmcnt(3)
	v_mfma_f32_32x32x16_bf16 v[36:51], v[172:175], v[88:91], v[36:51]
	v_add_f32_e32 v176, v60, v176
	v_add_f32_e32 v176, v61, v176
	v_add_f32_e32 v176, v62, v176
	v_add_f32_e32 v176, v63, v176
	v_add_f32_e32 v176, v64, v176
	v_add_f32_e32 v176, v65, v176
	v_add_f32_e32 v176, v66, v176
	v_add_f32_e32 v176, v67, v176
	v_cvt_pk_bf16_f32 v214, v52, v53
	v_cvt_pk_bf16_f32 v215, v54, v55
	v_cvt_pk_bf16_f32 v216, v56, v57
	v_cvt_pk_bf16_f32 v217, v58, v59
	v_cvt_pk_bf16_f32 v218, v60, v61
	v_cvt_pk_bf16_f32 v219, v62, v63
	v_cvt_pk_bf16_f32 v220, v64, v65
	v_cvt_pk_bf16_f32 v221, v66, v67
	v_mfma_f32_32x32x16_bf16 v[2:17], v[198:201], v[214:217], v[2:17]
	ds_read_b128 v[198:201], v150 offset:26688
	s_waitcnt lgkmcnt(2)
	v_mfma_f32_32x32x16_bf16 v[18:33], v[206:209], v[214:217], v[18:33]
	ds_read_b128 v[206:209], v150 offset:31296
	v_exp_f32_e32 v36, v36
	v_exp_f32_e32 v37, v37
	v_exp_f32_e32 v38, v38
	v_exp_f32_e32 v39, v39
	v_exp_f32_e32 v40, v40
	v_exp_f32_e32 v41, v41
	v_mfma_f32_32x32x16_bf16 v[2:17], v[202:205], v[218:221], v[2:17]
	ds_read_b128 v[202:205], v150 offset:26720
	v_exp_f32_e32 v42, v42
	v_exp_f32_e32 v43, v43
	v_exp_f32_e32 v44, v44
	v_exp_f32_e32 v45, v45
	v_exp_f32_e32 v46, v46
	v_exp_f32_e32 v47, v47
	s_waitcnt lgkmcnt(3)
	v_mfma_f32_32x32x16_bf16 v[18:33], v[210:213], v[218:221], v[18:33]
	ds_read_b128 v[210:213], v150 offset:31328
	v_exp_f32_e32 v48, v48
	v_exp_f32_e32 v49, v49
	v_exp_f32_e32 v50, v50
	v_exp_f32_e32 v51, v51
	v_cvt_pk_bf16_f32 v222, v36, v37
	v_cvt_pk_bf16_f32 v223, v38, v39
	v_cvt_pk_bf16_f32 v224, v40, v41
	v_cvt_pk_bf16_f32 v225, v42, v43
	v_add_f32_e32 v177, v36, v37
	v_add_f32_e32 v177, v38, v177
	s_waitcnt lgkmcnt(3)
	v_mfma_f32_32x32x16_bf16 v[2:17], v[198:201], v[222:225], v[2:17]
	v_add_f32_e32 v177, v39, v177
	v_add_f32_e32 v177, v40, v177
	v_add_f32_e32 v177, v41, v177
	v_add_f32_e32 v177, v42, v177
	v_add_f32_e32 v177, v43, v177
	v_add_f32_e32 v177, v44, v177
	s_waitcnt lgkmcnt(2)
	v_mfma_f32_32x32x16_bf16 v[18:33], v[206:209], v[222:225], v[18:33]
	v_add_f32_e32 v177, v45, v177
	v_add_f32_e32 v177, v46, v177
	v_add_f32_e32 v177, v47, v177
	v_add_f32_e32 v177, v48, v177
	v_add_f32_e32 v177, v49, v177
	v_add_f32_e32 v177, v50, v177
	v_add_f32_e32 v177, v51, v177
	v_cvt_pk_bf16_f32 v226, v44, v45
	v_cvt_pk_bf16_f32 v227, v46, v47
	v_cvt_pk_bf16_f32 v228, v48, v49
	v_cvt_pk_bf16_f32 v229, v50, v51
	v_add_f32_e32 v176, v176, v177
	ds_bpermute_b32 v180, v143, v176
	s_waitcnt lgkmcnt(2)
	v_mfma_f32_32x32x16_bf16 v[2:17], v[202:205], v[226:229], v[2:17]
	v_fma_f32 v140, v140, v138, v176
	s_waitcnt lgkmcnt(1)
	v_mfma_f32_32x32x16_bf16 v[18:33], v[210:213], v[226:229], v[18:33]
	s_waitcnt lgkmcnt(0)
	v_add_f32_e32 v180, v176, v180
	v_frexp_exp_i32_f32_e32 v178, v180
	v_cmp_lt_f32_e32 vcc, 0x46800000, v180
	v_cvt_f32_i32_e32 v178, v178
	s_nop 0
	v_cndmask_b32_e32 v181, 0, v178, vcc
	v_add_f32_e32 v141, v141, v181
	v_exp_f32_e64 v138, -v181
	s_add_i32 s36, s35, 4
	s_min_u32 s41, s36, 0x7f
	s_mul_i32 s36, s41, 0x3000
	s_add_u32 s36, s16, s36
	s_addc_u32 s37, s17, 0
	s_waitcnt lgkmcnt(0)
	s_barrier
; #define M2_STORE(S, buf) { M2_SK(0, S##k0, buf) M2_SK(1, S##k1, buf) M2_SK(2, S##k2, buf) M2_SV(0, S##v0, buf) M2_SV(1, S##v1, buf) }
; DI void flash_mla2(const bf16_t* __restrict__ Qp, const bf16_t* __restrict__ Kp, const bf16_t* __restrict__ Vtp,
;                    bf16_t* __restrict__ Op, char* smem, float& ssq) {
;     ...
;         M2_STORE(a, 0);
;         __syncthreads();
;         M2_LOAD(a, min(kt + 2, NKT - 1));
;         M2_COMPUTE(0);
;         M2_STORE(b, 1);
;         __syncthreads();
;         M2_LOAD(b, min(kt + 3, NKT - 1));
;         M2_COMPUTE(1);
	s_waitcnt vmcnt(9)
	ds_write_b128 v144, v[92:95]
	s_waitcnt vmcnt(8)
	ds_write_b128 v145, v[100:103]
	s_waitcnt vmcnt(6)
	ds_write_b128 v146, v[96:99]
	ds_write_b128 v147, v[104:107] offset:26624
	s_waitcnt vmcnt(5)
	ds_write_b128 v148, v[108:111] offset:26624
	global_load_dwordx4 v[92:95], v136, s[36:37]
	global_load_dwordx4 v[100:103], v137, s[36:37] offset:-4096
	global_load_dwordx4 v[96:99], v137, s[36:37]
	s_lshl_b32 s36, s41, 13
	s_add_u32 s36, s18, s36
	s_addc_u32 s37, s19, 0
	s_add_u32 s36, s36, 0x800
	s_addc_u32 s37, s37, 0
	global_load_dwordx4 v[104:107], v151, s[36:37] offset:-2048
	global_load_dwordx4 v[108:111], v151, s[36:37] offset:2048
	v_cmp_neq_f32_e32 vcc, 1.0, v138
	s_cbranch_vccz .Lmla_c1
	v_pk_mul_f32 v[32:33], v[138:139], v[32:33] op_sel_hi:[0,1]
	v_pk_mul_f32 v[30:31], v[138:139], v[30:31] op_sel_hi:[0,1]
	v_pk_mul_f32 v[28:29], v[138:139], v[28:29] op_sel_hi:[0,1]
	v_pk_mul_f32 v[26:27], v[138:139], v[26:27] op_sel_hi:[0,1]
	v_pk_mul_f32 v[24:25], v[138:139], v[24:25] op_sel_hi:[0,1]
	v_pk_mul_f32 v[22:23], v[138:139], v[22:23] op_sel_hi:[0,1]
	v_pk_mul_f32 v[20:21], v[138:139], v[20:21] op_sel_hi:[0,1]
	v_pk_mul_f32 v[18:19], v[138:139], v[18:19] op_sel_hi:[0,1]
	v_pk_mul_f32 v[16:17], v[138:139], v[16:17] op_sel_hi:[0,1]
	v_pk_mul_f32 v[14:15], v[138:139], v[14:15] op_sel_hi:[0,1]
	v_pk_mul_f32 v[12:13], v[138:139], v[12:13] op_sel_hi:[0,1]
	v_pk_mul_f32 v[10:11], v[138:139], v[10:11] op_sel_hi:[0,1]
	v_pk_mul_f32 v[8:9], v[138:139], v[8:9] op_sel_hi:[0,1]
	v_pk_mul_f32 v[6:7], v[138:139], v[6:7] op_sel_hi:[0,1]
	v_pk_mul_f32 v[4:5], v[138:139], v[4:5] op_sel_hi:[0,1]
	v_pk_mul_f32 v[2:3], v[138:139], v[2:3] op_sel_hi:[0,1]
	v_xor_b32_e32 v179, 0x80000000, v141
	v_mov_b32_e32 v232, v179
	v_mov_b32_e32 v233, v179
	v_mov_b32_e32 v234, v179
	v_mov_b32_e32 v235, v179
	v_mov_b32_e32 v236, v179
	v_mov_b32_e32 v237, v179
	v_mov_b32_e32 v238, v179
	v_mov_b32_e32 v239, v179
	v_mov_b32_e32 v240, v179
	v_mov_b32_e32 v241, v179
	v_mov_b32_e32 v242, v179
	v_mov_b32_e32 v243, v179
	v_mov_b32_e32 v244, v179
	v_mov_b32_e32 v245, v179
	v_mov_b32_e32 v246, v179
	v_mov_b32_e32 v247, v179
; #define M2_STORE(S, buf) { M2_SK(0, S##k0, buf) M2_SK(1, S##k1, buf) M2_SK(2, S##k2, buf) M2_SV(0, S##v0, buf) M2_SV(1, S##v1, buf) }
; DI void flash_mla2(const bf16_t* __restrict__ Qp, const bf16_t* __restrict__ Kp, const bf16_t* __restrict__ Vtp,
;                    bf16_t* __restrict__ Op, char* smem, float& ssq) {
;     ...
;         M2_STORE(b, 1);
;         __syncthreads();
;         M2_LOAD(b, min(kt + 3, NKT - 1));
;         M2_COMPUTE(1);
;     }
.Lmla_c1:
	ds_read_b128 v[152:155], v149 offset:13312
	ds_read_b128 v[156:159], v149 offset:13344
	ds_read_b128 v[160:163], v149 offset:13376
	ds_read_b128 v[164:167], v149 offset:13408
	ds_read_b128 v[168:171], v149 offset:13440
	ds_read_b128 v[172:175], v149 offset:13472
	s_waitcnt lgkmcnt(5)
	v_mfma_f32_32x32x16_bf16 v[52:67], v[152:155], v[68:71], v[232:247]
	ds_read_b128 v[152:155], v149 offset:19968
	s_waitcnt lgkmcnt(5)
	v_mfma_f32_32x32x16_bf16 v[52:67], v[156:159], v[72:75], v[52:67]
	ds_read_b128 v[156:159], v149 offset:20000
	s_waitcnt lgkmcnt(5)
	v_mfma_f32_32x32x16_bf16 v[52:67], v[160:163], v[76:79], v[52:67]
	ds_read_b128 v[160:163], v149 offset:20032
	s_waitcnt lgkmcnt(5)
	v_mfma_f32_32x32x16_bf16 v[52:67], v[164:167], v[80:83], v[52:67]
	ds_read_b128 v[164:167], v149 offset:20064
	s_waitcnt lgkmcnt(5)
	v_mfma_f32_32x32x16_bf16 v[52:67], v[168:171], v[84:87], v[52:67]
	ds_read_b128 v[168:171], v149 offset:20096
	ds_read_b128 v[198:201], v150 offset:35840
	s_waitcnt lgkmcnt(6)
	v_mfma_f32_32x32x16_bf16 v[52:67], v[172:175], v[88:91], v[52:67]
	ds_read_b128 v[172:175], v149 offset:20128
	ds_read_b128 v[202:205], v150 offset:35872
	ds_read_b128 v[206:209], v150 offset:40448
	ds_read_b128 v[210:213], v150 offset:40480
	s_waitcnt lgkmcnt(9)
	v_mfma_f32_32x32x16_bf16 v[36:51], v[152:155], v[68:71], v[232:247]
	s_waitcnt lgkmcnt(8)
	v_mfma_f32_32x32x16_bf16 v[36:51], v[156:159], v[72:75], v[36:51]
	s_nop 3
	v_exp_f32_e32 v52, v52
	v_exp_f32_e32 v53, v53
	s_waitcnt lgkmcnt(7)
	v_mfma_f32_32x32x16_bf16 v[36:51], v[160:163], v[76:79], v[36:51]
	v_exp_f32_e32 v54, v54
	v_exp_f32_e32 v55, v55
	v_exp_f32_e32 v56, v56
	v_exp_f32_e32 v57, v57
	v_exp_f32_e32 v58, v58
	v_exp_f32_e32 v59, v59
	s_waitcnt lgkmcnt(6)
	v_mfma_f32_32x32x16_bf16 v[36:51], v[164:167], v[80:83], v[36:51]
	v_exp_f32_e32 v60, v60
	v_exp_f32_e32 v61, v61
	v_exp_f32_e32 v62, v62
	v_exp_f32_e32 v63, v63
	v_exp_f32_e32 v64, v64
	v_exp_f32_e32 v65, v65
	s_waitcnt lgkmcnt(5)
	v_mfma_f32_32x32x16_bf16 v[36:51], v[168:171], v[84:87], v[36:51]
	v_exp_f32_e32 v66, v66
	v_exp_f32_e32 v67, v67
	v_add_f32_e32 v176, v52, v53
	v_add_f32_e32 v176, v54, v176
	v_add_f32_e32 v176, v55, v176
	v_add_f32_e32 v176, v56, v176
	v_add_f32_e32 v176, v57, v176
	v_add_f32_e32 v176, v58, v176
	v_add_f32_e32 v176, v59, v176
	s_waitcnt lgkmcnt(3)
	v_mfma_f32_32x32x16_bf16 v[36:51], v[172:175], v[88:91], v[36:51]
	v_add_f32_e32 v176, v60, v176
	v_add_f32_e32 v176, v61, v176
	v_add_f32_e32 v176, v62, v176
	v_add_f32_e32 v176, v63, v176
	v_add_f32_e32 v176, v64, v176
	v_add_f32_e32 v176, v65, v176
	v_add_f32_e32 v176, v66, v176
	v_add_f32_e32 v176, v67, v176
	v_cvt_pk_bf16_f32 v214, v52, v53
	v_cvt_pk_bf16_f32 v215, v54, v55
	v_cvt_pk_bf16_f32 v216, v56, v57
	v_cvt_pk_bf16_f32 v217, v58, v59
	v_cvt_pk_bf16_f32 v218, v60, v61
	v_cvt_pk_bf16_f32 v219, v62, v63
	v_cvt_pk_bf16_f32 v220, v64, v65
	v_cvt_pk_bf16_f32 v221, v66, v67
	v_mfma_f32_32x32x16_bf16 v[2:17], v[198:201], v[214:217], v[2:17]
	ds_read_b128 v[198:201], v150 offset:35904
	s_waitcnt lgkmcnt(2)
	v_mfma_f32_32x32x16_bf16 v[18:33], v[206:209], v[214:217], v[18:33]
	ds_read_b128 v[206:209], v150 offset:40512
	v_exp_f32_e32 v36, v36
	v_exp_f32_e32 v37, v37
	v_exp_f32_e32 v38, v38
	v_exp_f32_e32 v39, v39
	v_exp_f32_e32 v40, v40
	v_exp_f32_e32 v41, v41
	v_mfma_f32_32x32x16_bf16 v[2:17], v[202:205], v[218:221], v[2:17]
	ds_read_b128 v[202:205], v150 offset:35936
	v_exp_f32_e32 v42, v42
	v_exp_f32_e32 v43, v43
	v_exp_f32_e32 v44, v44
	v_exp_f32_e32 v45, v45
	v_exp_f32_e32 v46, v46
	v_exp_f32_e32 v47, v47
	s_waitcnt lgkmcnt(3)
	v_mfma_f32_32x32x16_bf16 v[18:33], v[210:213], v[218:221], v[18:33]
	ds_read_b128 v[210:213], v150 offset:40544
	v_exp_f32_e32 v48, v48
	v_exp_f32_e32 v49, v49
	v_exp_f32_e32 v50, v50
	v_exp_f32_e32 v51, v51
	v_cvt_pk_bf16_f32 v222, v36, v37
	v_cvt_pk_bf16_f32 v223, v38, v39
	v_cvt_pk_bf16_f32 v224, v40, v41
	v_cvt_pk_bf16_f32 v225, v42, v43
	v_add_f32_e32 v177, v36, v37
	v_add_f32_e32 v177, v38, v177
	s_waitcnt lgkmcnt(3)
	v_mfma_f32_32x32x16_bf16 v[2:17], v[198:201], v[222:225], v[2:17]
	v_add_f32_e32 v177, v39, v177
	v_add_f32_e32 v177, v40, v177
	v_add_f32_e32 v177, v41, v177
	v_add_f32_e32 v177, v42, v177
	v_add_f32_e32 v177, v43, v177
	v_add_f32_e32 v177, v44, v177
	s_waitcnt lgkmcnt(2)
	v_mfma_f32_32x32x16_bf16 v[18:33], v[206:209], v[222:225], v[18:33]
	v_add_f32_e32 v177, v45, v177
	v_add_f32_e32 v177, v46, v177
	v_add_f32_e32 v177, v47, v177
	v_add_f32_e32 v177, v48, v177
	v_add_f32_e32 v177, v49, v177
	v_add_f32_e32 v177, v50, v177
	v_add_f32_e32 v177, v51, v177
	v_cvt_pk_bf16_f32 v226, v44, v45
	v_cvt_pk_bf16_f32 v227, v46, v47
	v_cvt_pk_bf16_f32 v228, v48, v49
	v_cvt_pk_bf16_f32 v229, v50, v51
	v_add_f32_e32 v176, v176, v177
	ds_bpermute_b32 v180, v143, v176
	s_waitcnt lgkmcnt(2)
	v_mfma_f32_32x32x16_bf16 v[2:17], v[202:205], v[226:229], v[2:17]
	v_fma_f32 v140, v140, v138, v176
	s_waitcnt lgkmcnt(1)
	v_mfma_f32_32x32x16_bf16 v[18:33], v[210:213], v[226:229], v[18:33]
	s_waitcnt lgkmcnt(0)
	v_add_f32_e32 v180, v176, v180
	v_frexp_exp_i32_f32_e32 v178, v180
	v_cmp_lt_f32_e32 vcc, 0x46800000, v180
	v_cvt_f32_i32_e32 v178, v178
	s_nop 0
	v_cndmask_b32_e32 v181, 0, v178, vcc
	v_add_f32_e32 v141, v141, v181
	v_exp_f32_e64 v138, -v181
	s_cmpk_lt_u32 s35, 0x7e
	s_cbranch_scc1 .LBB0_184
	s_branch .LBB0_181
